# LR2 epilogue: the four 8-byte row stores of a row block paired into two dwordx4 stores via v_permlane16_swap
# speedup vs baseline: 1.0079x; 1.0079x over previous
.LBB0_2040:
	s_andn2_b64 vcc, exec, s[0:1]
	s_cbranch_vccnz .LBB0_2977
	s_cmp_lt_i32 s79, 2
	s_mov_b64 s[0:1], -1
	s_cbranch_scc1 .LBB0_2072
	s_cmp_gt_i32 s79, 2
	s_cbranch_scc0 .LBB0_2055
	s_add_i32 s0, s91, 0x20098
	v_mov_b32_e32 v0, s0
	s_add_i32 s0, s91, 0x2009c
	v_mov_b32_e32 v1, s0
	s_add_i32 s0, s91, 0x200b0
	v_mov_b32_e32 v2, s0
	s_add_i32 s0, s91, 0x200b4
	v_mov_b32_e32 v3, s0
	ds_read_b32 v0, v0
	ds_read_b32 v1, v1
	ds_read_b32 v2, v2
	ds_read_b32 v3, v3
	v_readlane_b32 s0, v254, 20
	s_waitcnt lgkmcnt(0)
	v_readfirstlane_b32 s2, v0
	v_readfirstlane_b32 s3, v1
	v_readfirstlane_b32 s8, v2
	v_readfirstlane_b32 s9, v3
	s_cmpk_gt_i32 s0, 0x41ff
	v_and_b32_e32 v134, 15, v162
	v_readlane_b32 s1, v254, 21
	s_cbranch_scc1 .LBB0_2048
	v_readlane_b32 s0, v254, 26
	v_readlane_b32 s14, v254, 20
	s_lshl_b32 s4, s0, 11
	s_ashr_i32 s0, s14, 31
	s_lshr_b32 s0, s0, 26
	s_add_i32 s0, s14, s0
	s_and_b32 s1, s0, 0xffffffc0
	s_sub_i32 s5, s14, s1
	s_lshr_b32 s0, s5, 4
	s_bfe_i32 s6, s0, 0x80000
	s_bfe_u32 s6, s6, 0x2000d
	s_add_i32 s6, s0, s6
	s_and_b32 s6, s6, 0xfc
	s_sub_i32 s0, s0, s6
	s_sext_i32_i8 s0, s0
	s_lshl_b32 s0, s0, 6
	v_or_b32_e32 v8, s1, v134
	s_ashr_i32 s1, s0, 31
	s_lshl_b64 s[0:1], s[0:1], 1
	v_readlane_b32 s6, v254, 34
	v_readlane_b32 s7, v254, 35
	s_add_u32 s0, s6, s0
	s_addc_u32 s1, s7, s1
	v_and_b32_e32 v152, 48, v164
	v_lshl_add_u64 v[0:1], s[0:1], 0, v[152:153]
	v_readlane_b32 s0, v254, 32
	v_lshl_or_b32 v2, s5, 6, v134
	v_readlane_b32 s1, v254, 33
	v_ashrrev_i32_e32 v3, 31, v2
	v_lshrrev_b32_e32 v64, 2, v164
	v_lshl_add_u64 v[4:5], s[0:1], 0, v[152:153]
	s_mov_b64 s[0:1], 0x14980000
	v_lshl_add_u64 v[128:129], v[4:5], 0, s[0:1]
	v_lshlrev_b64 v[4:5], 7, v[2:3]
	v_or_b32_e32 v3, 16, v8
	s_waitcnt vmcnt(0)
	v_mad_i64_i32 v[12:13], s[0:1], v3, s95, v[0:1]
	v_or_b32_e32 v3, 32, v8
	v_mad_i64_i32 v[20:21], s[0:1], v3, s95, v[0:1]
	v_or_b32_e32 v3, 48, v8
	v_mad_i64_i32 v[6:7], s[0:1], v8, s95, v[0:1]
	v_mad_i64_i32 v[28:29], s[0:1], v3, s95, v[0:1]
	v_or_b32_e32 v0, 16, v2
	v_ashrrev_i32_e32 v1, 31, v0
	v_lshlrev_b64 v[0:1], 7, v[0:1]
	v_lshl_add_u64 v[44:45], v[128:129], 0, v[0:1]
	v_or_b32_e32 v0, 32, v2
	v_ashrrev_i32_e32 v1, 31, v0
	v_lshlrev_b64 v[0:1], 7, v[0:1]
	v_lshl_add_u64 v[52:53], v[128:129], 0, v[0:1]
	v_or_b32_e32 v0, 48, v2
	v_ashrrev_i32_e32 v1, 31, v0
	v_lshlrev_b64 v[0:1], 7, v[0:1]
	v_lshl_add_u64 v[36:37], v[128:129], 0, v[4:5]
	v_lshl_add_u64 v[60:61], v[128:129], 0, v[0:1]
	global_load_dwordx4 v[0:3], v[6:7], off
	s_nop 0
	global_load_dwordx4 v[4:7], v[6:7], off offset:64
	s_nop 0
	global_load_dwordx4 v[8:11], v[12:13], off
	s_nop 0
	global_load_dwordx4 v[12:15], v[12:13], off offset:64
	s_nop 0
	global_load_dwordx4 v[16:19], v[20:21], off
	s_nop 0
	global_load_dwordx4 v[20:23], v[20:21], off offset:64
	s_nop 0
	global_load_dwordx4 v[24:27], v[28:29], off
	s_nop 0
	global_load_dwordx4 v[28:31], v[28:29], off offset:64
	s_nop 0
	global_load_dwordx4 v[32:35], v[36:37], off
	s_nop 0
	global_load_dwordx4 v[36:39], v[36:37], off offset:64
	s_nop 0
	global_load_dwordx4 v[40:43], v[44:45], off
	s_nop 0
	global_load_dwordx4 v[44:47], v[44:45], off offset:64
	s_nop 0
	global_load_dwordx4 v[48:51], v[52:53], off
	s_nop 0
	global_load_dwordx4 v[52:55], v[52:53], off offset:64
	s_nop 0
	global_load_dwordx4 v[56:59], v[60:61], off
	s_nop 0
	global_load_dwordx4 v[60:63], v[60:61], off offset:64
	v_readlane_b32 s0, v254, 22
	s_lshl_b32 s11, s0, 6
	v_lshl_add_u64 v[130:131], s[6:7], 0, v[152:153]
	v_and_b32_e32 v135, 12, v64
	s_lshl_b32 s10, s14, 6
	v_or_b32_e32 v136, s11, v134
	s_lshl_b32 s12, s4, 2
	s_mov_b32 s4, s14
	v_readlane_b32 s15, v254, 21
	v_readlane_b32 s1, v254, 23
	v_mbcnt_lo_u32_b32 v212, -1, 0
	v_mbcnt_hi_u32_b32 v212, -1, v212
	v_and_b32_e32 v212, 16, v212
	v_lshrrev_b32_e32 v213, 1, v212
	v_add_u32_e32 v212, v212, v213
	v_mov_b32_e32 v213, 0
	s_waitcnt vmcnt(0)
	s_branch .LBB0_2046
.LBB0_2045:
	s_ashr_i32 s5, s4, 31
	s_lshr_b32 s5, s5, 26
	s_add_i32 s5, s4, s5
	s_andn2_b32 s5, s5, 63
	s_sub_i32 s4, s4, s5
	s_ashr_i32 s14, s4, 4
	v_or_b32_e32 v132, s5, v134
	s_cmp_eq_u32 s14, 2
	s_mov_b32 s5, 0x8400000
	s_cselect_b32 s5, 0x4200000, s5
	s_cmp_lg_u32 s14, 1
	s_cselect_b32 s5, s5, 0x6300000
	s_cmp_gt_u32 s4, 15
	s_cselect_b32 s4, s5, 0x2100000
	s_and_b32 s5, s10, 0x3c0
	v_readlane_b32 s6, v254, 32
	v_readlane_b32 s7, v254, 33
	s_add_u32 s6, s6, s4
	s_addc_u32 s7, s7, 0
	s_cmp_lt_i32 s14, 2
	s_cselect_b64 vcc, -1, 0
	v_or_b32_e32 v137, s5, v135
	s_and_b64 s[4:5], vcc, exec
	s_cselect_b32 s5, s2, s8
	s_cselect_b32 s4, s3, s9
	s_add_u32 s5, s5, s12
	s_addc_u32 s15, s4, 0
	s_lshl_b32 s4, s14, 12
	s_and_b32 s4, s4, 0x1000
	v_ashrrev_i32_e32 v133, 31, v132
	s_add_u32 s4, s5, s4
	v_lshlrev_b64 v[138:139], 11, v[132:133]
	s_addc_u32 s5, s15, 0
	v_lshlrev_b32_e32 v133, 2, v137
	v_lshl_add_u64 v[142:143], s[6:7], 0, v[138:139]
	v_lshlrev_b32_e32 v152, 1, v137
	s_add_i32 s10, s10, s11
	v_add_f32_e32 v124, v124, v188
	v_mul_f32_e32 v124, 0xbfb8aa3b, v124
	v_exp_f32_e32 v124, v124
	s_nop 0
	v_add_f32_e32 v124, 1.0, v124
	v_rcp_f32_e32 v124, v124
	s_nop 0
	v_mul_f32_e32 v138, 0xbf1b4598, v124
	v_mul_f32_e32 v138, 0x3fb8aa3b, v138
	v_exp_f32_e32 v138, v138
	s_nop 0
	v_sub_f32_e32 v138, 1.0, v138
	v_cndmask_b32_e32 v138, v124, v138, vcc
	v_add_f32_e32 v124, v125, v189
	v_mul_f32_e32 v124, 0xbfb8aa3b, v124
	v_exp_f32_e32 v124, v124
	s_nop 0
	v_add_f32_e32 v124, 1.0, v124
	v_rcp_f32_e32 v124, v124
	s_nop 0
	v_mul_f32_e32 v125, 0xbf1b4598, v124
	v_mul_f32_e32 v125, 0x3fb8aa3b, v125
	v_exp_f32_e32 v125, v125
	s_nop 0
	v_sub_f32_e32 v125, 1.0, v125
	v_cndmask_b32_e32 v139, v124, v125, vcc
	v_add_f32_e32 v124, v126, v190
	v_mul_f32_e32 v124, 0xbfb8aa3b, v124
	v_exp_f32_e32 v124, v124
	s_nop 0
	v_add_f32_e32 v124, 1.0, v124
	v_rcp_f32_e32 v124, v124
	s_nop 0
	v_mul_f32_e32 v125, 0xbf1b4598, v124
	v_mul_f32_e32 v125, 0x3fb8aa3b, v125
	v_exp_f32_e32 v125, v125
	s_nop 0
	v_sub_f32_e32 v125, 1.0, v125
	v_cndmask_b32_e32 v126, v124, v125, vcc
	v_add_f32_e32 v124, v127, v191
	v_mul_f32_e32 v124, 0xbfb8aa3b, v124
	v_exp_f32_e32 v124, v124
	s_nop 0
	v_add_f32_e32 v124, 1.0, v124
	v_rcp_f32_e32 v124, v124
	s_nop 0
	v_mul_f32_e32 v125, 0xbf1b4598, v124
	v_mul_f32_e32 v125, 0x3fb8aa3b, v125
	v_exp_f32_e32 v125, v125
	s_nop 0
	v_sub_f32_e32 v125, 1.0, v125
	v_cndmask_b32_e32 v127, v124, v125, vcc
	v_lshl_add_u64 v[124:125], v[142:143], 0, v[152:153]
	v_cvt_pk_f16_f32 v127, v126, v127
	v_cvt_pk_f16_f32 v126, v138, v139
	v_mov_b32_e32 v206, v126
	v_mov_b32_e32 v207, v127
	v_add_f32_e32 v120, v120, v192
	v_mul_f32_e32 v120, 0xbfb8aa3b, v120
	v_exp_f32_e32 v120, v120
	v_add_f32_e32 v121, v121, v193
	v_mul_f32_e32 v121, 0xbfb8aa3b, v121
	v_exp_f32_e32 v121, v121
	v_add_f32_e32 v120, 1.0, v120
	v_rcp_f32_e32 v120, v120
	v_add_f32_e32 v121, 1.0, v121
	v_rcp_f32_e32 v121, v121
	v_mul_f32_e32 v126, 0xbf1b4598, v120
	v_mul_f32_e32 v126, 0x3fb8aa3b, v126
	v_exp_f32_e32 v126, v126
	s_nop 0
	v_sub_f32_e32 v126, 1.0, v126
	v_cndmask_b32_e32 v120, v120, v126, vcc
	v_mul_f32_e32 v126, 0xbf1b4598, v121
	v_mul_f32_e32 v126, 0x3fb8aa3b, v126
	v_exp_f32_e32 v126, v126
	s_nop 0
	v_sub_f32_e32 v126, 1.0, v126
	v_cndmask_b32_e32 v126, v121, v126, vcc
	v_add_f32_e32 v121, v122, v194
	v_mul_f32_e32 v121, 0xbfb8aa3b, v121
	v_exp_f32_e32 v121, v121
	v_cvt_pk_f16_f32 v120, v120, v126
	v_add_f32_e32 v121, 1.0, v121
	v_rcp_f32_e32 v121, v121
	s_nop 0
	v_mul_f32_e32 v122, 0xbf1b4598, v121
	v_mul_f32_e32 v122, 0x3fb8aa3b, v122
	v_exp_f32_e32 v122, v122
	s_nop 0
	v_sub_f32_e32 v122, 1.0, v122
	v_cndmask_b32_e32 v121, v121, v122, vcc
	v_add_f32_e32 v122, v123, v195
	v_mul_f32_e32 v122, 0xbfb8aa3b, v122
	v_exp_f32_e32 v122, v122
	s_nop 0
	v_add_f32_e32 v122, 1.0, v122
	v_rcp_f32_e32 v122, v122
	s_nop 0
	v_mul_f32_e32 v123, 0xbf1b4598, v122
	v_mul_f32_e32 v123, 0x3fb8aa3b, v123
	v_exp_f32_e32 v123, v123
	s_nop 0
	v_sub_f32_e32 v123, 1.0, v123
	v_cndmask_b32_e32 v122, v122, v123, vcc
	v_cvt_pk_f16_f32 v121, v121, v122
	v_mov_b32_e32 v208, v120
	v_mov_b32_e32 v209, v121
	v_lshl_add_u64 v[210:211], v[212:213], 0, v[124:125]
	s_nop 0
	v_permlane16_swap_b32 v206, v208
	v_permlane16_swap_b32 v207, v209
	global_store_dwordx4 v[210:211], v[206:209], off
	v_add_f32_e32 v116, v116, v196
	v_mul_f32_e32 v116, 0xbfb8aa3b, v116
	v_exp_f32_e32 v116, v116
	v_add_f32_e32 v117, v117, v197
	v_mul_f32_e32 v117, 0xbfb8aa3b, v117
	v_exp_f32_e32 v117, v117
	v_add_f32_e32 v116, 1.0, v116
	v_rcp_f32_e32 v116, v116
	v_add_f32_e32 v117, 1.0, v117
	v_rcp_f32_e32 v117, v117
	v_mul_f32_e32 v120, 0xbf1b4598, v116
	v_mul_f32_e32 v120, 0x3fb8aa3b, v120
	v_exp_f32_e32 v120, v120
	s_nop 0
	v_sub_f32_e32 v120, 1.0, v120
	v_cndmask_b32_e32 v116, v116, v120, vcc
	v_mul_f32_e32 v120, 0xbf1b4598, v117
	v_mul_f32_e32 v120, 0x3fb8aa3b, v120
	v_exp_f32_e32 v120, v120
	s_nop 0
	v_sub_f32_e32 v120, 1.0, v120
	v_cndmask_b32_e32 v120, v117, v120, vcc
	v_add_f32_e32 v117, v118, v198
	v_mul_f32_e32 v117, 0xbfb8aa3b, v117
	v_exp_f32_e32 v117, v117
	v_cvt_pk_f16_f32 v116, v116, v120
	v_add_f32_e32 v117, 1.0, v117
	v_rcp_f32_e32 v117, v117
	s_nop 0
	v_mul_f32_e32 v118, 0xbf1b4598, v117
	v_mul_f32_e32 v118, 0x3fb8aa3b, v118
	v_exp_f32_e32 v118, v118
	s_nop 0
	v_sub_f32_e32 v118, 1.0, v118
	v_cndmask_b32_e32 v117, v117, v118, vcc
	v_add_f32_e32 v118, v119, v199
	v_mul_f32_e32 v118, 0xbfb8aa3b, v118
	v_exp_f32_e32 v118, v118
	s_nop 0
	v_add_f32_e32 v118, 1.0, v118
	v_rcp_f32_e32 v118, v118
	s_nop 0
	v_mul_f32_e32 v119, 0xbf1b4598, v118
	v_mul_f32_e32 v119, 0x3fb8aa3b, v119
	v_exp_f32_e32 v119, v119
	s_nop 0
	v_sub_f32_e32 v119, 1.0, v119
	v_cndmask_b32_e32 v118, v118, v119, vcc
	v_cvt_pk_f16_f32 v117, v117, v118
	v_mov_b32_e32 v206, v116
	v_mov_b32_e32 v207, v117
	v_add_f32_e32 v112, v112, v200
	v_mul_f32_e32 v112, 0xbfb8aa3b, v112
	v_exp_f32_e32 v112, v112
	v_add_f32_e32 v113, v113, v201
	v_mul_f32_e32 v113, 0xbfb8aa3b, v113
	v_exp_f32_e32 v113, v113
	v_add_f32_e32 v112, 1.0, v112
	v_rcp_f32_e32 v112, v112
	v_add_f32_e32 v113, 1.0, v113
	v_rcp_f32_e32 v113, v113
	v_mul_f32_e32 v116, 0xbf1b4598, v112
	v_mul_f32_e32 v116, 0x3fb8aa3b, v116
	v_exp_f32_e32 v116, v116
	s_nop 0
	v_sub_f32_e32 v116, 1.0, v116
	v_cndmask_b32_e32 v112, v112, v116, vcc
	v_mul_f32_e32 v116, 0xbf1b4598, v113
	v_mul_f32_e32 v116, 0x3fb8aa3b, v116
	v_exp_f32_e32 v116, v116
	s_nop 0
	v_sub_f32_e32 v116, 1.0, v116
	v_cndmask_b32_e32 v116, v113, v116, vcc
	v_add_f32_e32 v113, v114, v202
	v_mul_f32_e32 v113, 0xbfb8aa3b, v113
	v_exp_f32_e32 v113, v113
	v_cvt_pk_f16_f32 v112, v112, v116
	v_add_f32_e32 v113, 1.0, v113
	v_rcp_f32_e32 v113, v113
	s_nop 0
	v_mul_f32_e32 v114, 0xbf1b4598, v113
	v_mul_f32_e32 v114, 0x3fb8aa3b, v114
	v_exp_f32_e32 v114, v114
	s_nop 0
	v_sub_f32_e32 v114, 1.0, v114
	v_cndmask_b32_e32 v113, v113, v114, vcc
	v_add_f32_e32 v114, v115, v203
	v_mul_f32_e32 v114, 0xbfb8aa3b, v114
	v_exp_f32_e32 v114, v114
	s_nop 0
	v_add_f32_e32 v114, 1.0, v114
	v_rcp_f32_e32 v114, v114
	s_nop 0
	v_mul_f32_e32 v115, 0xbf1b4598, v114
	v_mul_f32_e32 v115, 0x3fb8aa3b, v115
	v_exp_f32_e32 v115, v115
	s_nop 0
	v_sub_f32_e32 v115, 1.0, v115
	v_cndmask_b32_e32 v114, v114, v115, vcc
	v_cvt_pk_f16_f32 v113, v113, v114
	v_mov_b32_e32 v208, v112
	v_mov_b32_e32 v209, v113
	v_lshl_add_u64 v[210:211], v[212:213], 0, v[124:125]
	s_nop 0
	v_permlane16_swap_b32 v206, v208
	v_permlane16_swap_b32 v207, v209
	global_store_dwordx4 v[210:211], v[206:209], off offset:64
	v_or_b32_e32 v112, 16, v132
	v_ashrrev_i32_e32 v113, 31, v112
	v_lshlrev_b64 v[112:113], 11, v[112:113]
	v_lshl_add_u64 v[116:117], s[6:7], 0, v[112:113]
	v_add_f32_e32 v108, v108, v188
	v_mul_f32_e32 v108, 0xbfb8aa3b, v108
	v_exp_f32_e32 v108, v108
	s_nop 0
	v_add_f32_e32 v108, 1.0, v108
	v_rcp_f32_e32 v108, v108
	s_nop 0
	v_mul_f32_e32 v112, 0xbf1b4598, v108
	v_mul_f32_e32 v112, 0x3fb8aa3b, v112
	v_exp_f32_e32 v112, v112
	s_nop 0
	v_sub_f32_e32 v112, 1.0, v112
	v_cndmask_b32_e32 v112, v108, v112, vcc
	v_add_f32_e32 v108, v109, v189
	v_mul_f32_e32 v108, 0xbfb8aa3b, v108
	v_exp_f32_e32 v108, v108
	s_nop 0
	v_add_f32_e32 v108, 1.0, v108
	v_rcp_f32_e32 v108, v108
	s_nop 0
	v_mul_f32_e32 v109, 0xbf1b4598, v108
	v_mul_f32_e32 v109, 0x3fb8aa3b, v109
	v_exp_f32_e32 v109, v109
	s_nop 0
	v_sub_f32_e32 v109, 1.0, v109
	v_cndmask_b32_e32 v113, v108, v109, vcc
	v_add_f32_e32 v108, v110, v190
	v_mul_f32_e32 v108, 0xbfb8aa3b, v108
	v_exp_f32_e32 v108, v108
	s_nop 0
	v_add_f32_e32 v108, 1.0, v108
	v_rcp_f32_e32 v108, v108
	s_nop 0
	v_mul_f32_e32 v109, 0xbf1b4598, v108
	v_mul_f32_e32 v109, 0x3fb8aa3b, v109
	v_exp_f32_e32 v109, v109
	s_nop 0
	v_sub_f32_e32 v109, 1.0, v109
	v_cndmask_b32_e32 v110, v108, v109, vcc
	v_add_f32_e32 v108, v111, v191
	v_mul_f32_e32 v108, 0xbfb8aa3b, v108
	v_exp_f32_e32 v108, v108
	s_nop 0
	v_add_f32_e32 v108, 1.0, v108
	v_rcp_f32_e32 v108, v108
	s_nop 0
	v_mul_f32_e32 v109, 0xbf1b4598, v108
	v_mul_f32_e32 v109, 0x3fb8aa3b, v109
	v_exp_f32_e32 v109, v109
	s_nop 0
	v_sub_f32_e32 v109, 1.0, v109
	v_cndmask_b32_e32 v111, v108, v109, vcc
	v_lshl_add_u64 v[108:109], v[116:117], 0, v[152:153]
	v_cvt_pk_f16_f32 v111, v110, v111
	v_cvt_pk_f16_f32 v110, v112, v113
	v_mov_b32_e32 v206, v110
	v_mov_b32_e32 v207, v111
	v_add_f32_e32 v104, v104, v192
	v_mul_f32_e32 v104, 0xbfb8aa3b, v104
	v_exp_f32_e32 v104, v104
	v_add_f32_e32 v105, v105, v193
	v_mul_f32_e32 v105, 0xbfb8aa3b, v105
	v_exp_f32_e32 v105, v105
	v_add_f32_e32 v104, 1.0, v104
	v_rcp_f32_e32 v104, v104
	v_add_f32_e32 v105, 1.0, v105
	v_rcp_f32_e32 v105, v105
	v_mul_f32_e32 v110, 0xbf1b4598, v104
	v_mul_f32_e32 v110, 0x3fb8aa3b, v110
	v_exp_f32_e32 v110, v110
	s_nop 0
	v_sub_f32_e32 v110, 1.0, v110
	v_cndmask_b32_e32 v104, v104, v110, vcc
	v_mul_f32_e32 v110, 0xbf1b4598, v105
	v_mul_f32_e32 v110, 0x3fb8aa3b, v110
	v_exp_f32_e32 v110, v110
	s_nop 0
	v_sub_f32_e32 v110, 1.0, v110
	v_cndmask_b32_e32 v110, v105, v110, vcc
	v_add_f32_e32 v105, v106, v194
	v_mul_f32_e32 v105, 0xbfb8aa3b, v105
	v_exp_f32_e32 v105, v105
	v_cvt_pk_f16_f32 v104, v104, v110
	v_add_f32_e32 v105, 1.0, v105
	v_rcp_f32_e32 v105, v105
	s_nop 0
	v_mul_f32_e32 v106, 0xbf1b4598, v105
	v_mul_f32_e32 v106, 0x3fb8aa3b, v106
	v_exp_f32_e32 v106, v106
	s_nop 0
	v_sub_f32_e32 v106, 1.0, v106
	v_cndmask_b32_e32 v105, v105, v106, vcc
	v_add_f32_e32 v106, v107, v195
	v_mul_f32_e32 v106, 0xbfb8aa3b, v106
	v_exp_f32_e32 v106, v106
	s_nop 0
	v_add_f32_e32 v106, 1.0, v106
	v_rcp_f32_e32 v106, v106
	s_nop 0
	v_mul_f32_e32 v107, 0xbf1b4598, v106
	v_mul_f32_e32 v107, 0x3fb8aa3b, v107
	v_exp_f32_e32 v107, v107
	s_nop 0
	v_sub_f32_e32 v107, 1.0, v107
	v_cndmask_b32_e32 v106, v106, v107, vcc
	v_cvt_pk_f16_f32 v105, v105, v106
	v_mov_b32_e32 v208, v104
	v_mov_b32_e32 v209, v105
	v_lshl_add_u64 v[210:211], v[212:213], 0, v[108:109]
	s_nop 0
	v_permlane16_swap_b32 v206, v208
	v_permlane16_swap_b32 v207, v209
	global_store_dwordx4 v[210:211], v[206:209], off
	v_add_f32_e32 v100, v100, v196
	v_mul_f32_e32 v100, 0xbfb8aa3b, v100
	v_exp_f32_e32 v100, v100
	v_add_f32_e32 v101, v101, v197
	v_mul_f32_e32 v101, 0xbfb8aa3b, v101
	v_exp_f32_e32 v101, v101
	v_add_f32_e32 v100, 1.0, v100
	v_rcp_f32_e32 v100, v100
	v_add_f32_e32 v101, 1.0, v101
	v_rcp_f32_e32 v101, v101
	v_mul_f32_e32 v104, 0xbf1b4598, v100
	v_mul_f32_e32 v104, 0x3fb8aa3b, v104
	v_exp_f32_e32 v104, v104
	s_nop 0
	v_sub_f32_e32 v104, 1.0, v104
	v_cndmask_b32_e32 v100, v100, v104, vcc
	v_mul_f32_e32 v104, 0xbf1b4598, v101
	v_mul_f32_e32 v104, 0x3fb8aa3b, v104
	v_exp_f32_e32 v104, v104
	s_nop 0
	v_sub_f32_e32 v104, 1.0, v104
	v_cndmask_b32_e32 v104, v101, v104, vcc
	v_add_f32_e32 v101, v102, v198
	v_mul_f32_e32 v101, 0xbfb8aa3b, v101
	v_exp_f32_e32 v101, v101
	v_cvt_pk_f16_f32 v100, v100, v104
	v_add_f32_e32 v101, 1.0, v101
	v_rcp_f32_e32 v101, v101
	s_nop 0
	v_mul_f32_e32 v102, 0xbf1b4598, v101
	v_mul_f32_e32 v102, 0x3fb8aa3b, v102
	v_exp_f32_e32 v102, v102
	s_nop 0
	v_sub_f32_e32 v102, 1.0, v102
	v_cndmask_b32_e32 v101, v101, v102, vcc
	v_add_f32_e32 v102, v103, v199
	v_mul_f32_e32 v102, 0xbfb8aa3b, v102
	v_exp_f32_e32 v102, v102
	s_nop 0
	v_add_f32_e32 v102, 1.0, v102
	v_rcp_f32_e32 v102, v102
	s_nop 0
	v_mul_f32_e32 v103, 0xbf1b4598, v102
	v_mul_f32_e32 v103, 0x3fb8aa3b, v103
	v_exp_f32_e32 v103, v103
	s_nop 0
	v_sub_f32_e32 v103, 1.0, v103
	v_cndmask_b32_e32 v102, v102, v103, vcc
	v_cvt_pk_f16_f32 v101, v101, v102
	v_mov_b32_e32 v206, v100
	v_mov_b32_e32 v207, v101
	v_add_f32_e32 v96, v96, v200
	v_mul_f32_e32 v96, 0xbfb8aa3b, v96
	v_exp_f32_e32 v96, v96
	v_add_f32_e32 v97, v97, v201
	v_mul_f32_e32 v97, 0xbfb8aa3b, v97
	v_exp_f32_e32 v97, v97
	v_add_f32_e32 v96, 1.0, v96
	v_rcp_f32_e32 v96, v96
	v_add_f32_e32 v97, 1.0, v97
	v_rcp_f32_e32 v97, v97
	v_mul_f32_e32 v100, 0xbf1b4598, v96
	v_mul_f32_e32 v100, 0x3fb8aa3b, v100
	v_exp_f32_e32 v100, v100
	s_nop 0
	v_sub_f32_e32 v100, 1.0, v100
	v_cndmask_b32_e32 v96, v96, v100, vcc
	v_mul_f32_e32 v100, 0xbf1b4598, v97
	v_mul_f32_e32 v100, 0x3fb8aa3b, v100
	v_exp_f32_e32 v100, v100
	s_nop 0
	v_sub_f32_e32 v100, 1.0, v100
	v_cndmask_b32_e32 v100, v97, v100, vcc
	v_add_f32_e32 v97, v98, v202
	v_mul_f32_e32 v97, 0xbfb8aa3b, v97
	v_exp_f32_e32 v97, v97
	v_cvt_pk_f16_f32 v96, v96, v100
	v_add_f32_e32 v97, 1.0, v97
	v_rcp_f32_e32 v97, v97
	s_nop 0
	v_mul_f32_e32 v98, 0xbf1b4598, v97
	v_mul_f32_e32 v98, 0x3fb8aa3b, v98
	v_exp_f32_e32 v98, v98
	s_nop 0
	v_sub_f32_e32 v98, 1.0, v98
	v_cndmask_b32_e32 v97, v97, v98, vcc
	v_add_f32_e32 v98, v99, v203
	v_mul_f32_e32 v98, 0xbfb8aa3b, v98
	v_exp_f32_e32 v98, v98
	s_nop 0
	v_add_f32_e32 v98, 1.0, v98
	v_rcp_f32_e32 v98, v98
	s_nop 0
	v_mul_f32_e32 v99, 0xbf1b4598, v98
	v_mul_f32_e32 v99, 0x3fb8aa3b, v99
	v_exp_f32_e32 v99, v99
	s_nop 0
	v_sub_f32_e32 v99, 1.0, v99
	v_cndmask_b32_e32 v98, v98, v99, vcc
	v_cvt_pk_f16_f32 v97, v97, v98
	v_mov_b32_e32 v208, v96
	v_mov_b32_e32 v209, v97
	v_lshl_add_u64 v[210:211], v[212:213], 0, v[108:109]
	s_nop 0
	v_permlane16_swap_b32 v206, v208
	v_permlane16_swap_b32 v207, v209
	global_store_dwordx4 v[210:211], v[206:209], off offset:64
	v_or_b32_e32 v96, 32, v132
	v_ashrrev_i32_e32 v97, 31, v96
	v_lshlrev_b64 v[96:97], 11, v[96:97]
	v_lshl_add_u64 v[100:101], s[6:7], 0, v[96:97]
	v_add_f32_e32 v92, v92, v188
	v_mul_f32_e32 v92, 0xbfb8aa3b, v92
	v_exp_f32_e32 v92, v92
	s_nop 0
	v_add_f32_e32 v92, 1.0, v92
	v_rcp_f32_e32 v92, v92
	s_nop 0
	v_mul_f32_e32 v96, 0xbf1b4598, v92
	v_mul_f32_e32 v96, 0x3fb8aa3b, v96
	v_exp_f32_e32 v96, v96
	s_nop 0
	v_sub_f32_e32 v96, 1.0, v96
	v_cndmask_b32_e32 v96, v92, v96, vcc
	v_add_f32_e32 v92, v93, v189
	v_mul_f32_e32 v92, 0xbfb8aa3b, v92
	v_exp_f32_e32 v92, v92
	s_nop 0
	v_add_f32_e32 v92, 1.0, v92
	v_rcp_f32_e32 v92, v92
	s_nop 0
	v_mul_f32_e32 v93, 0xbf1b4598, v92
	v_mul_f32_e32 v93, 0x3fb8aa3b, v93
	v_exp_f32_e32 v93, v93
	s_nop 0
	v_sub_f32_e32 v93, 1.0, v93
	v_cndmask_b32_e32 v97, v92, v93, vcc
	v_add_f32_e32 v92, v94, v190
	v_mul_f32_e32 v92, 0xbfb8aa3b, v92
	v_exp_f32_e32 v92, v92
	s_nop 0
	v_add_f32_e32 v92, 1.0, v92
	v_rcp_f32_e32 v92, v92
	s_nop 0
	v_mul_f32_e32 v93, 0xbf1b4598, v92
	v_mul_f32_e32 v93, 0x3fb8aa3b, v93
	v_exp_f32_e32 v93, v93
	s_nop 0
	v_sub_f32_e32 v93, 1.0, v93
	v_cndmask_b32_e32 v94, v92, v93, vcc
	v_add_f32_e32 v92, v95, v191
	v_mul_f32_e32 v92, 0xbfb8aa3b, v92
	v_exp_f32_e32 v92, v92
	s_nop 0
	v_add_f32_e32 v92, 1.0, v92
	v_rcp_f32_e32 v92, v92
	s_nop 0
	v_mul_f32_e32 v93, 0xbf1b4598, v92
	v_mul_f32_e32 v93, 0x3fb8aa3b, v93
	v_exp_f32_e32 v93, v93
	s_nop 0
	v_sub_f32_e32 v93, 1.0, v93
	v_cndmask_b32_e32 v95, v92, v93, vcc
	v_lshl_add_u64 v[92:93], v[100:101], 0, v[152:153]
	v_cvt_pk_f16_f32 v95, v94, v95
	v_cvt_pk_f16_f32 v94, v96, v97
	v_mov_b32_e32 v206, v94
	v_mov_b32_e32 v207, v95
	v_add_f32_e32 v88, v88, v192
	v_mul_f32_e32 v88, 0xbfb8aa3b, v88
	v_exp_f32_e32 v88, v88
	v_add_f32_e32 v89, v89, v193
	v_mul_f32_e32 v89, 0xbfb8aa3b, v89
	v_exp_f32_e32 v89, v89
	v_add_f32_e32 v88, 1.0, v88
	v_rcp_f32_e32 v88, v88
	v_add_f32_e32 v89, 1.0, v89
	v_rcp_f32_e32 v89, v89
	v_mul_f32_e32 v94, 0xbf1b4598, v88
	v_mul_f32_e32 v94, 0x3fb8aa3b, v94
	v_exp_f32_e32 v94, v94
	s_nop 0
	v_sub_f32_e32 v94, 1.0, v94
	v_cndmask_b32_e32 v88, v88, v94, vcc
	v_mul_f32_e32 v94, 0xbf1b4598, v89
	v_mul_f32_e32 v94, 0x3fb8aa3b, v94
	v_exp_f32_e32 v94, v94
	s_nop 0
	v_sub_f32_e32 v94, 1.0, v94
	v_cndmask_b32_e32 v94, v89, v94, vcc
	v_add_f32_e32 v89, v90, v194
	v_mul_f32_e32 v89, 0xbfb8aa3b, v89
	v_exp_f32_e32 v89, v89
	v_cvt_pk_f16_f32 v88, v88, v94
	v_add_f32_e32 v89, 1.0, v89
	v_rcp_f32_e32 v89, v89
	s_nop 0
	v_mul_f32_e32 v90, 0xbf1b4598, v89
	v_mul_f32_e32 v90, 0x3fb8aa3b, v90
	v_exp_f32_e32 v90, v90
	s_nop 0
	v_sub_f32_e32 v90, 1.0, v90
	v_cndmask_b32_e32 v89, v89, v90, vcc
	v_add_f32_e32 v90, v91, v195
	v_mul_f32_e32 v90, 0xbfb8aa3b, v90
	v_exp_f32_e32 v90, v90
	s_nop 0
	v_add_f32_e32 v90, 1.0, v90
	v_rcp_f32_e32 v90, v90
	s_nop 0
	v_mul_f32_e32 v91, 0xbf1b4598, v90
	v_mul_f32_e32 v91, 0x3fb8aa3b, v91
	v_exp_f32_e32 v91, v91
	s_nop 0
	v_sub_f32_e32 v91, 1.0, v91
	v_cndmask_b32_e32 v90, v90, v91, vcc
	v_cvt_pk_f16_f32 v89, v89, v90
	v_mov_b32_e32 v208, v88
	v_mov_b32_e32 v209, v89
	v_lshl_add_u64 v[210:211], v[212:213], 0, v[92:93]
	s_nop 0
	v_permlane16_swap_b32 v206, v208
	v_permlane16_swap_b32 v207, v209
	global_store_dwordx4 v[210:211], v[206:209], off
	v_add_f32_e32 v84, v84, v196
	v_mul_f32_e32 v84, 0xbfb8aa3b, v84
	v_exp_f32_e32 v84, v84
	v_add_f32_e32 v85, v85, v197
	v_mul_f32_e32 v85, 0xbfb8aa3b, v85
	v_exp_f32_e32 v85, v85
	v_add_f32_e32 v84, 1.0, v84
	v_rcp_f32_e32 v84, v84
	v_add_f32_e32 v85, 1.0, v85
	v_rcp_f32_e32 v85, v85
	v_mul_f32_e32 v88, 0xbf1b4598, v84
	v_mul_f32_e32 v88, 0x3fb8aa3b, v88
	v_exp_f32_e32 v88, v88
	s_nop 0
	v_sub_f32_e32 v88, 1.0, v88
	v_cndmask_b32_e32 v84, v84, v88, vcc
	v_mul_f32_e32 v88, 0xbf1b4598, v85
	v_mul_f32_e32 v88, 0x3fb8aa3b, v88
	v_exp_f32_e32 v88, v88
	s_nop 0
	v_sub_f32_e32 v88, 1.0, v88
	v_cndmask_b32_e32 v88, v85, v88, vcc
	v_add_f32_e32 v85, v86, v198
	v_mul_f32_e32 v85, 0xbfb8aa3b, v85
	v_exp_f32_e32 v85, v85
	v_cvt_pk_f16_f32 v84, v84, v88
	v_add_f32_e32 v85, 1.0, v85
	v_rcp_f32_e32 v85, v85
	s_nop 0
	v_mul_f32_e32 v86, 0xbf1b4598, v85
	v_mul_f32_e32 v86, 0x3fb8aa3b, v86
	v_exp_f32_e32 v86, v86
	s_nop 0
	v_sub_f32_e32 v86, 1.0, v86
	v_cndmask_b32_e32 v85, v85, v86, vcc
	v_add_f32_e32 v86, v87, v199
	v_mul_f32_e32 v86, 0xbfb8aa3b, v86
	v_exp_f32_e32 v86, v86
	s_nop 0
	v_add_f32_e32 v86, 1.0, v86
	v_rcp_f32_e32 v86, v86
	s_nop 0
	v_mul_f32_e32 v87, 0xbf1b4598, v86
	v_mul_f32_e32 v87, 0x3fb8aa3b, v87
	v_exp_f32_e32 v87, v87
	s_nop 0
	v_sub_f32_e32 v87, 1.0, v87
	v_cndmask_b32_e32 v86, v86, v87, vcc
	v_cvt_pk_f16_f32 v85, v85, v86
	v_mov_b32_e32 v206, v84
	v_mov_b32_e32 v207, v85
	v_add_f32_e32 v80, v80, v200
	v_mul_f32_e32 v80, 0xbfb8aa3b, v80
	v_exp_f32_e32 v80, v80
	v_add_f32_e32 v81, v81, v201
	v_mul_f32_e32 v81, 0xbfb8aa3b, v81
	v_exp_f32_e32 v81, v81
	v_add_f32_e32 v80, 1.0, v80
	v_rcp_f32_e32 v80, v80
	v_add_f32_e32 v81, 1.0, v81
	v_rcp_f32_e32 v81, v81
	v_mul_f32_e32 v84, 0xbf1b4598, v80
	v_mul_f32_e32 v84, 0x3fb8aa3b, v84
	v_exp_f32_e32 v84, v84
	s_nop 0
	v_sub_f32_e32 v84, 1.0, v84
	v_cndmask_b32_e32 v80, v80, v84, vcc
	v_mul_f32_e32 v84, 0xbf1b4598, v81
	v_mul_f32_e32 v84, 0x3fb8aa3b, v84
	v_exp_f32_e32 v84, v84
	s_nop 0
	v_sub_f32_e32 v84, 1.0, v84
	v_cndmask_b32_e32 v84, v81, v84, vcc
	v_add_f32_e32 v81, v82, v202
	v_mul_f32_e32 v81, 0xbfb8aa3b, v81
	v_exp_f32_e32 v81, v81
	v_cvt_pk_f16_f32 v80, v80, v84
	v_add_f32_e32 v81, 1.0, v81
	v_rcp_f32_e32 v81, v81
	s_nop 0
	v_mul_f32_e32 v82, 0xbf1b4598, v81
	v_mul_f32_e32 v82, 0x3fb8aa3b, v82
	v_exp_f32_e32 v82, v82
	s_nop 0
	v_sub_f32_e32 v82, 1.0, v82
	v_cndmask_b32_e32 v81, v81, v82, vcc
	v_add_f32_e32 v82, v83, v203
	v_mul_f32_e32 v82, 0xbfb8aa3b, v82
	v_exp_f32_e32 v82, v82
	s_nop 0
	v_add_f32_e32 v82, 1.0, v82
	v_rcp_f32_e32 v82, v82
	s_nop 0
	v_mul_f32_e32 v83, 0xbf1b4598, v82
	v_mul_f32_e32 v83, 0x3fb8aa3b, v83
	v_exp_f32_e32 v83, v83
	s_nop 0
	v_sub_f32_e32 v83, 1.0, v83
	v_cndmask_b32_e32 v82, v82, v83, vcc
	v_cvt_pk_f16_f32 v81, v81, v82
	v_mov_b32_e32 v208, v80
	v_mov_b32_e32 v209, v81
	v_lshl_add_u64 v[210:211], v[212:213], 0, v[92:93]
	s_nop 0
	v_permlane16_swap_b32 v206, v208
	v_permlane16_swap_b32 v207, v209
	global_store_dwordx4 v[210:211], v[206:209], off offset:64
	v_or_b32_e32 v80, 48, v132
	v_ashrrev_i32_e32 v81, 31, v80
	v_lshlrev_b64 v[80:81], 11, v[80:81]
	v_lshl_add_u64 v[84:85], s[6:7], 0, v[80:81]
	v_add_f32_e32 v76, v76, v188
	v_mul_f32_e32 v76, 0xbfb8aa3b, v76
	v_exp_f32_e32 v76, v76
	s_nop 0
	v_add_f32_e32 v76, 1.0, v76
	v_rcp_f32_e32 v76, v76
	s_nop 0
	v_mul_f32_e32 v80, 0xbf1b4598, v76
	v_mul_f32_e32 v80, 0x3fb8aa3b, v80
	v_exp_f32_e32 v80, v80
	s_nop 0
	v_sub_f32_e32 v80, 1.0, v80
	v_cndmask_b32_e32 v80, v76, v80, vcc
	v_add_f32_e32 v76, v77, v189
	v_mul_f32_e32 v76, 0xbfb8aa3b, v76
	v_exp_f32_e32 v76, v76
	s_nop 0
	v_add_f32_e32 v76, 1.0, v76
	v_rcp_f32_e32 v76, v76
	s_nop 0
	v_mul_f32_e32 v77, 0xbf1b4598, v76
	v_mul_f32_e32 v77, 0x3fb8aa3b, v77
	v_exp_f32_e32 v77, v77
	s_nop 0
	v_sub_f32_e32 v77, 1.0, v77
	v_cndmask_b32_e32 v81, v76, v77, vcc
	v_add_f32_e32 v76, v78, v190
	v_mul_f32_e32 v76, 0xbfb8aa3b, v76
	v_exp_f32_e32 v76, v76
	s_nop 0
	v_add_f32_e32 v76, 1.0, v76
	v_rcp_f32_e32 v76, v76
	s_nop 0
	v_mul_f32_e32 v77, 0xbf1b4598, v76
	v_mul_f32_e32 v77, 0x3fb8aa3b, v77
	v_exp_f32_e32 v77, v77
	s_nop 0
	v_sub_f32_e32 v77, 1.0, v77
	v_cndmask_b32_e32 v78, v76, v77, vcc
	v_add_f32_e32 v76, v79, v191
	v_mul_f32_e32 v76, 0xbfb8aa3b, v76
	v_exp_f32_e32 v76, v76
	s_nop 0
	v_add_f32_e32 v76, 1.0, v76
	v_rcp_f32_e32 v76, v76
	s_nop 0
	v_mul_f32_e32 v77, 0xbf1b4598, v76
	v_mul_f32_e32 v77, 0x3fb8aa3b, v77
	v_exp_f32_e32 v77, v77
	s_nop 0
	v_sub_f32_e32 v77, 1.0, v77
	v_cndmask_b32_e32 v79, v76, v77, vcc
	v_lshl_add_u64 v[76:77], v[84:85], 0, v[152:153]
	v_cvt_pk_f16_f32 v79, v78, v79
	v_cvt_pk_f16_f32 v78, v80, v81
	v_mov_b32_e32 v206, v78
	v_mov_b32_e32 v207, v79
	v_add_f32_e32 v72, v72, v192
	v_mul_f32_e32 v72, 0xbfb8aa3b, v72
	v_exp_f32_e32 v72, v72
	v_add_f32_e32 v73, v73, v193
	v_mul_f32_e32 v73, 0xbfb8aa3b, v73
	v_exp_f32_e32 v73, v73
	v_add_f32_e32 v72, 1.0, v72
	v_rcp_f32_e32 v72, v72
	v_add_f32_e32 v73, 1.0, v73
	v_rcp_f32_e32 v73, v73
	v_mul_f32_e32 v78, 0xbf1b4598, v72
	v_mul_f32_e32 v78, 0x3fb8aa3b, v78
	v_exp_f32_e32 v78, v78
	s_nop 0
	v_sub_f32_e32 v78, 1.0, v78
	v_cndmask_b32_e32 v72, v72, v78, vcc
	v_mul_f32_e32 v78, 0xbf1b4598, v73
	v_mul_f32_e32 v78, 0x3fb8aa3b, v78
	v_exp_f32_e32 v78, v78
	s_nop 0
	v_sub_f32_e32 v78, 1.0, v78
	v_cndmask_b32_e32 v78, v73, v78, vcc
	v_add_f32_e32 v73, v74, v194
	v_mul_f32_e32 v73, 0xbfb8aa3b, v73
	v_exp_f32_e32 v73, v73
	v_cvt_pk_f16_f32 v72, v72, v78
	v_add_f32_e32 v73, 1.0, v73
	v_rcp_f32_e32 v73, v73
	s_nop 0
	v_mul_f32_e32 v74, 0xbf1b4598, v73
	v_mul_f32_e32 v74, 0x3fb8aa3b, v74
	v_exp_f32_e32 v74, v74
	s_nop 0
	v_sub_f32_e32 v74, 1.0, v74
	v_cndmask_b32_e32 v73, v73, v74, vcc
	v_add_f32_e32 v74, v75, v195
	v_mul_f32_e32 v74, 0xbfb8aa3b, v74
	v_exp_f32_e32 v74, v74
	s_nop 0
	v_add_f32_e32 v74, 1.0, v74
	v_rcp_f32_e32 v74, v74
	s_nop 0
	v_mul_f32_e32 v75, 0xbf1b4598, v74
	v_mul_f32_e32 v75, 0x3fb8aa3b, v75
	v_exp_f32_e32 v75, v75
	s_nop 0
	v_sub_f32_e32 v75, 1.0, v75
	v_cndmask_b32_e32 v74, v74, v75, vcc
	v_cvt_pk_f16_f32 v73, v73, v74
	v_mov_b32_e32 v208, v72
	v_mov_b32_e32 v209, v73
	v_lshl_add_u64 v[210:211], v[212:213], 0, v[76:77]
	s_nop 0
	v_permlane16_swap_b32 v206, v208
	v_permlane16_swap_b32 v207, v209
	global_store_dwordx4 v[210:211], v[206:209], off
	v_add_f32_e32 v68, v68, v196
	v_mul_f32_e32 v68, 0xbfb8aa3b, v68
	v_exp_f32_e32 v68, v68
	v_add_f32_e32 v69, v69, v197
	v_mul_f32_e32 v69, 0xbfb8aa3b, v69
	v_exp_f32_e32 v69, v69
	v_add_f32_e32 v68, 1.0, v68
	v_rcp_f32_e32 v68, v68
	v_add_f32_e32 v69, 1.0, v69
	v_rcp_f32_e32 v69, v69
	v_mul_f32_e32 v72, 0xbf1b4598, v68
	v_mul_f32_e32 v72, 0x3fb8aa3b, v72
	v_exp_f32_e32 v72, v72
	s_nop 0
	v_sub_f32_e32 v72, 1.0, v72
	v_cndmask_b32_e32 v68, v68, v72, vcc
	v_mul_f32_e32 v72, 0xbf1b4598, v69
	v_mul_f32_e32 v72, 0x3fb8aa3b, v72
	v_exp_f32_e32 v72, v72
	s_nop 0
	v_sub_f32_e32 v72, 1.0, v72
	v_cndmask_b32_e32 v72, v69, v72, vcc
	v_add_f32_e32 v69, v70, v198
	v_mul_f32_e32 v69, 0xbfb8aa3b, v69
	v_exp_f32_e32 v69, v69
	v_cvt_pk_f16_f32 v68, v68, v72
	v_add_f32_e32 v69, 1.0, v69
	v_rcp_f32_e32 v69, v69
	s_nop 0
	v_mul_f32_e32 v70, 0xbf1b4598, v69
	v_mul_f32_e32 v70, 0x3fb8aa3b, v70
	v_exp_f32_e32 v70, v70
	s_nop 0
	v_sub_f32_e32 v70, 1.0, v70
	v_cndmask_b32_e32 v69, v69, v70, vcc
	v_add_f32_e32 v70, v71, v199
	v_mul_f32_e32 v70, 0xbfb8aa3b, v70
	v_exp_f32_e32 v70, v70
	s_nop 0
	v_add_f32_e32 v70, 1.0, v70
	v_rcp_f32_e32 v70, v70
	s_nop 0
	v_mul_f32_e32 v71, 0xbf1b4598, v70
	v_mul_f32_e32 v71, 0x3fb8aa3b, v71
	v_exp_f32_e32 v71, v71
	s_nop 0
	v_sub_f32_e32 v71, 1.0, v71
	v_cndmask_b32_e32 v70, v70, v71, vcc
	v_cvt_pk_f16_f32 v69, v69, v70
	v_mov_b32_e32 v206, v68
	v_mov_b32_e32 v207, v69
	s_mov_b32 s4, s13
	v_add_f32_e32 v64, v64, v200
	v_mul_f32_e32 v64, 0xbfb8aa3b, v64
	v_exp_f32_e32 v64, v64
	v_add_f32_e32 v65, v65, v201
	v_mul_f32_e32 v65, 0xbfb8aa3b, v65
	v_exp_f32_e32 v65, v65
	v_add_f32_e32 v64, 1.0, v64
	v_rcp_f32_e32 v64, v64
	v_add_f32_e32 v65, 1.0, v65
	v_rcp_f32_e32 v65, v65
	v_mul_f32_e32 v68, 0xbf1b4598, v64
	v_mul_f32_e32 v68, 0x3fb8aa3b, v68
	v_exp_f32_e32 v68, v68
	s_nop 0
	v_sub_f32_e32 v68, 1.0, v68
	v_cndmask_b32_e32 v64, v64, v68, vcc
	v_mul_f32_e32 v68, 0xbf1b4598, v65
	v_mul_f32_e32 v68, 0x3fb8aa3b, v68
	v_exp_f32_e32 v68, v68
	s_nop 0
	v_sub_f32_e32 v68, 1.0, v68
	v_cndmask_b32_e32 v68, v65, v68, vcc
	v_add_f32_e32 v65, v66, v202
	v_mul_f32_e32 v65, 0xbfb8aa3b, v65
	v_exp_f32_e32 v65, v65
	v_cvt_pk_f16_f32 v64, v64, v68
	v_add_f32_e32 v65, 1.0, v65
	v_rcp_f32_e32 v65, v65
	s_nop 0
	v_mul_f32_e32 v66, 0xbf1b4598, v65
	v_mul_f32_e32 v66, 0x3fb8aa3b, v66
	v_exp_f32_e32 v66, v66
	s_nop 0
	v_sub_f32_e32 v66, 1.0, v66
	v_cndmask_b32_e32 v65, v65, v66, vcc
	v_add_f32_e32 v66, v67, v203
	v_mul_f32_e32 v66, 0xbfb8aa3b, v66
	v_exp_f32_e32 v66, v66
	s_nop 0
	v_add_f32_e32 v66, 1.0, v66
	v_rcp_f32_e32 v66, v66
	s_nop 0
	v_mul_f32_e32 v67, 0xbf1b4598, v66
	v_mul_f32_e32 v67, 0x3fb8aa3b, v67
	v_exp_f32_e32 v67, v67
	s_nop 0
	v_sub_f32_e32 v67, 1.0, v67
	v_cndmask_b32_e32 v66, v66, v67, vcc
	v_cvt_pk_f16_f32 v65, v65, v66
	s_andn2_b64 vcc, exec, s[0:1]
	v_mov_b32_e32 v208, v64
	v_mov_b32_e32 v209, v65
	v_lshl_add_u64 v[210:211], v[212:213], 0, v[76:77]
	s_nop 0
	v_permlane16_swap_b32 v206, v208
	v_permlane16_swap_b32 v207, v209
	global_store_dwordx4 v[210:211], v[206:209], off offset:64
	s_cbranch_vccz .LBB0_2048
.LBB0_2046:
	s_waitcnt vmcnt(15)
	v_mfma_f32_16x16x32_bf16 v[64:67], v[32:35], v[0:3], 0
	v_readlane_b32 s0, v254, 22
	s_add_i32 s13, s4, s0
	v_readlane_b32 s1, v254, 23
	s_waitcnt vmcnt(13)
	v_mfma_f32_16x16x32_bf16 v[68:71], v[40:43], v[0:3], 0
	s_cmpk_gt_i32 s13, 0x41ff
	s_cselect_b64 s[0:1], -1, 0
	s_and_b64 vcc, exec, s[0:1]
	s_waitcnt vmcnt(11)
	v_mfma_f32_16x16x32_bf16 v[72:75], v[48:51], v[0:3], 0
	s_waitcnt vmcnt(9)
	v_mfma_f32_16x16x32_bf16 v[76:79], v[56:59], v[0:3], 0
	v_mfma_f32_16x16x32_bf16 v[80:83], v[32:35], v[8:11], 0
	v_mfma_f32_16x16x32_bf16 v[84:87], v[40:43], v[8:11], 0
	v_mfma_f32_16x16x32_bf16 v[88:91], v[48:51], v[8:11], 0
	v_mfma_f32_16x16x32_bf16 v[92:95], v[56:59], v[8:11], 0
	v_mfma_f32_16x16x32_bf16 v[138:141], v[32:35], v[16:19], 0
	v_mfma_f32_16x16x32_bf16 v[142:145], v[40:43], v[16:19], 0
	v_mfma_f32_16x16x32_bf16 v[146:149], v[48:51], v[16:19], 0
	v_mfma_f32_16x16x32_bf16 v[166:169], v[56:59], v[16:19], 0
	v_mfma_f32_16x16x32_bf16 v[170:173], v[32:35], v[24:27], 0
	v_mfma_f32_16x16x32_bf16 v[174:177], v[40:43], v[24:27], 0
	v_mfma_f32_16x16x32_bf16 v[178:181], v[48:51], v[24:27], 0
	v_mfma_f32_16x16x32_bf16 v[182:185], v[56:59], v[24:27], 0
	v_mfma_f32_16x16x32_bf16 v[124:127], v[36:39], v[4:7], v[64:67]
	v_mfma_f32_16x16x32_bf16 v[120:123], v[44:47], v[4:7], v[68:71]
	v_mfma_f32_16x16x32_bf16 v[116:119], v[52:55], v[4:7], v[72:75]
	s_waitcnt vmcnt(8)
	v_mfma_f32_16x16x32_bf16 v[112:115], v[60:63], v[4:7], v[76:79]
	v_mfma_f32_16x16x32_bf16 v[108:111], v[36:39], v[12:15], v[80:83]
	v_mfma_f32_16x16x32_bf16 v[104:107], v[44:47], v[12:15], v[84:87]
	v_mfma_f32_16x16x32_bf16 v[100:103], v[52:55], v[12:15], v[88:91]
	v_mfma_f32_16x16x32_bf16 v[96:99], v[60:63], v[12:15], v[92:95]
	v_mfma_f32_16x16x32_bf16 v[92:95], v[36:39], v[20:23], v[138:141]
	v_mfma_f32_16x16x32_bf16 v[88:91], v[44:47], v[20:23], v[142:145]
	v_mfma_f32_16x16x32_bf16 v[84:87], v[52:55], v[20:23], v[146:149]
	v_mfma_f32_16x16x32_bf16 v[80:83], v[60:63], v[20:23], v[166:169]
	v_mfma_f32_16x16x32_bf16 v[76:79], v[36:39], v[28:31], v[170:173]
	v_mfma_f32_16x16x32_bf16 v[72:75], v[44:47], v[28:31], v[174:177]
	v_mfma_f32_16x16x32_bf16 v[68:71], v[52:55], v[28:31], v[178:181]
	v_mfma_f32_16x16x32_bf16 v[64:67], v[60:63], v[28:31], v[182:185]
	s_ashr_i32 s5, s4, 31
	s_lshr_b32 s5, s5, 26
	s_add_i32 s5, s4, s5
	s_andn2_b32 s5, s5, 63
	s_sub_i32 s14, s4, s5
	s_lshr_b32 s14, s14, 4
	s_and_b32 s5, s10, 0x3c0
	v_or_b32_e32 v204, s5, v135
	v_lshlrev_b32_e32 v204, 2, v204
	s_cmp_lt_i32 s14, 2
	s_cselect_b32 s6, s2, s8
	s_cselect_b32 s7, s3, s9
	s_add_u32 s6, s6, s12
	s_addc_u32 s7, s7, 0
	s_lshl_b32 s5, s14, 12
	s_and_b32 s5, s5, 0x1000
	s_add_u32 s6, s6, s5
	s_addc_u32 s7, s7, 0
	global_load_dwordx4 v[188:191], v204, s[6:7]
	global_load_dwordx4 v[192:195], v204, s[6:7] offset:64
	global_load_dwordx4 v[196:199], v204, s[6:7] offset:128
	global_load_dwordx4 v[200:203], v204, s[6:7] offset:192
	s_cbranch_vccnz .Llr_nopf
	s_ashr_i32 s5, s13, 31
	s_lshr_b32 s5, s5, 26
	s_add_i32 s5, s13, s5
	s_and_b32 s7, s5, 0xffffffc0
	s_sub_i32 s6, s13, s7
	s_lshr_b32 s6, s6, 4
	s_bfe_i32 s14, s6, 0x80000
	s_bfe_u32 s14, s14, 0x2000d
	s_add_i32 s14, s6, s14
	s_and_b32 s14, s14, 0xfc
	s_sub_i32 s6, s6, s14
	s_lshl_b32 s5, s5, 6
	s_sext_i32_i8 s6, s6
	v_add_u32_e32 v2, s10, v136
	s_and_b32 s5, s5, 0xfffff000
	s_lshl_b32 s6, s6, 6
	v_subrev_u32_e32 v2, s5, v2
	v_or_b32_e32 v8, s7, v134
	s_ashr_i32 s7, s6, 31
	v_ashrrev_i32_e32 v3, 31, v2
	v_lshl_add_u64 v[0:1], s[6:7], 1, v[130:131]
	v_lshlrev_b64 v[4:5], 7, v[2:3]
	v_or_b32_e32 v3, 16, v8
	v_mad_i64_i32 v[12:13], s[6:7], v3, s95, v[0:1]
	v_or_b32_e32 v3, 32, v8
	v_mad_i64_i32 v[20:21], s[6:7], v3, s95, v[0:1]
	v_or_b32_e32 v3, 48, v8
	v_mad_i64_i32 v[6:7], s[6:7], v8, s95, v[0:1]
	v_mad_i64_i32 v[28:29], s[6:7], v3, s95, v[0:1]
	v_add_u32_e32 v0, 16, v2
	v_ashrrev_i32_e32 v1, 31, v0
	v_lshlrev_b64 v[0:1], 7, v[0:1]
	v_lshl_add_u64 v[44:45], v[128:129], 0, v[0:1]
	v_add_u32_e32 v0, 32, v2
	v_ashrrev_i32_e32 v1, 31, v0
	v_lshlrev_b64 v[0:1], 7, v[0:1]
	v_lshl_add_u64 v[52:53], v[128:129], 0, v[0:1]
	v_add_u32_e32 v0, 48, v2
	v_ashrrev_i32_e32 v1, 31, v0
	v_lshlrev_b64 v[0:1], 7, v[0:1]
	v_lshl_add_u64 v[36:37], v[128:129], 0, v[4:5]
	v_lshl_add_u64 v[60:61], v[128:129], 0, v[0:1]
	global_load_dwordx4 v[0:3], v[6:7], off
	s_nop 0
	global_load_dwordx4 v[4:7], v[6:7], off offset:64
	s_nop 0
	global_load_dwordx4 v[8:11], v[12:13], off
	s_nop 0
	global_load_dwordx4 v[12:15], v[12:13], off offset:64
	s_nop 0
	global_load_dwordx4 v[16:19], v[20:21], off
	s_nop 0
	global_load_dwordx4 v[20:23], v[20:21], off offset:64
	s_nop 0
	global_load_dwordx4 v[24:27], v[28:29], off
	s_nop 0
	global_load_dwordx4 v[28:31], v[28:29], off offset:64
	s_nop 0
	global_load_dwordx4 v[32:35], v[36:37], off
	s_nop 0
	global_load_dwordx4 v[36:39], v[36:37], off offset:64
	s_nop 0
	global_load_dwordx4 v[40:43], v[44:45], off
	s_nop 0
	global_load_dwordx4 v[44:47], v[44:45], off offset:64
	s_nop 0
	global_load_dwordx4 v[48:51], v[52:53], off
	s_nop 0
	global_load_dwordx4 v[52:55], v[52:53], off offset:64
	s_nop 0
	global_load_dwordx4 v[56:59], v[60:61], off
	s_nop 0
	global_load_dwordx4 v[60:63], v[60:61], off offset:64
	s_waitcnt vmcnt(16)
	s_branch .LBB0_2045
